# hgrn inter-chunk scan: straight-line 32 steps with 16-step-deep load prefetch and counted vmcnt waits (was 2 steps ahead with a full drain every 8)
# speedup vs baseline: 1.0025x; 1.0025x over previous
.LBB0_615:
	v_ashrrev_i32_e32 v2, 12, v1
	v_ashrrev_i32_e32 v3, 31, v2
	v_lshlrev_b32_e32 v8, 1, v16
	v_lshlrev_b32_e32 v9, 2, v16
	v_lshlrev_b64 v[6:7], 14, v[2:3]
	v_lshlrev_b64 v[4:5], 20, v[2:3]
	v_and_or_b32 v4, v8, s15, v4
	v_and_or_b32 v6, v9, s16, v6
	v_mov_b32_e32 v12, 0
	v_lshl_add_u64 v[2:3], s[84:85], 0, v[4:5]
	v_lshl_add_u64 v[4:5], s[82:83], 0, v[4:5]
	v_lshl_add_u64 v[6:7], s[6:7], 0, v[6:7]
	s_mov_b64 s[12:13], 0
	v_mov_b32_e32 v13, v12
	v_mov_b32_e32 v14, v12
	v_mov_b32_e32 v15, v12
	s_waitcnt lgkmcnt(0)
	s_mov_b64 s[12:13], 0
	s_mov_b64 s[18:19], 0
	s_mov_b32 s22, 0xd000000
	s_mov_b32 s23, 0
	s_mov_b64 s[20:21], 0x2000
	v_lshl_add_u64 v[36:37], v[2:3], 0, s[22:23]
	v_lshl_add_u64 v[28:29], v[6:7], 0, s[20:21]
	v_lshl_add_u64 v[30:31], v[28:29], 0, s[20:21]
	v_lshl_add_u64 v[8:9], v[4:5], 0, s[12:13]
	global_load_dwordx2 v[40:41], v[8:9], off
	global_load_dwordx4 v[72:75], v[6:7], off offset:-3584
	s_add_u32 s12, s12, 0x8000
	s_addc_u32 s13, s13, 0
	v_lshl_add_u64 v[8:9], v[4:5], 0, s[12:13]
	global_load_dwordx2 v[42:43], v[8:9], off
	global_load_dwordx4 v[76:79], v[6:7], off offset:-3072
	s_add_u32 s12, s12, 0x8000
	s_addc_u32 s13, s13, 0
	v_lshl_add_u64 v[8:9], v[4:5], 0, s[12:13]
	global_load_dwordx2 v[44:45], v[8:9], off
	global_load_dwordx4 v[80:83], v[6:7], off offset:-2560
	s_add_u32 s12, s12, 0x8000
	s_addc_u32 s13, s13, 0
	v_lshl_add_u64 v[8:9], v[4:5], 0, s[12:13]
	global_load_dwordx2 v[46:47], v[8:9], off
	global_load_dwordx4 v[84:87], v[6:7], off offset:-2048
	s_add_u32 s12, s12, 0x8000
	s_addc_u32 s13, s13, 0
	v_lshl_add_u64 v[8:9], v[4:5], 0, s[12:13]
	global_load_dwordx2 v[48:49], v[8:9], off
	global_load_dwordx4 v[88:91], v[6:7], off offset:-1536
	s_add_u32 s12, s12, 0x8000
	s_addc_u32 s13, s13, 0
	v_lshl_add_u64 v[8:9], v[4:5], 0, s[12:13]
	global_load_dwordx2 v[50:51], v[8:9], off
	global_load_dwordx4 v[92:95], v[6:7], off offset:-1024
	s_add_u32 s12, s12, 0x8000
	s_addc_u32 s13, s13, 0
	v_lshl_add_u64 v[8:9], v[4:5], 0, s[12:13]
	global_load_dwordx2 v[52:53], v[8:9], off
	global_load_dwordx4 v[96:99], v[6:7], off offset:-512
	s_add_u32 s12, s12, 0x8000
	s_addc_u32 s13, s13, 0
	v_lshl_add_u64 v[8:9], v[4:5], 0, s[12:13]
	global_load_dwordx2 v[54:55], v[8:9], off
	global_load_dwordx4 v[100:103], v[6:7], off
	s_add_u32 s12, s12, 0x8000
	s_addc_u32 s13, s13, 0
	v_lshl_add_u64 v[8:9], v[4:5], 0, s[12:13]
	global_load_dwordx2 v[56:57], v[8:9], off
	global_load_dwordx4 v[104:107], v[6:7], off offset:512
	s_add_u32 s12, s12, 0x8000
	s_addc_u32 s13, s13, 0
	v_lshl_add_u64 v[8:9], v[4:5], 0, s[12:13]
	global_load_dwordx2 v[58:59], v[8:9], off
	global_load_dwordx4 v[108:111], v[6:7], off offset:1024
	s_add_u32 s12, s12, 0x8000
	s_addc_u32 s13, s13, 0
	v_lshl_add_u64 v[8:9], v[4:5], 0, s[12:13]
	global_load_dwordx2 v[60:61], v[8:9], off
	global_load_dwordx4 v[112:115], v[6:7], off offset:1536
	s_add_u32 s12, s12, 0x8000
	s_addc_u32 s13, s13, 0
	v_lshl_add_u64 v[8:9], v[4:5], 0, s[12:13]
	global_load_dwordx2 v[62:63], v[8:9], off
	global_load_dwordx4 v[116:119], v[6:7], off offset:2048
	s_add_u32 s12, s12, 0x8000
	s_addc_u32 s13, s13, 0
	v_lshl_add_u64 v[8:9], v[4:5], 0, s[12:13]
	global_load_dwordx2 v[64:65], v[8:9], off
	global_load_dwordx4 v[120:123], v[6:7], off offset:2560
	s_add_u32 s12, s12, 0x8000
	s_addc_u32 s13, s13, 0
	v_lshl_add_u64 v[8:9], v[4:5], 0, s[12:13]
	global_load_dwordx2 v[66:67], v[8:9], off
	global_load_dwordx4 v[124:127], v[6:7], off offset:3072
	s_add_u32 s12, s12, 0x8000
	s_addc_u32 s13, s13, 0
	v_lshl_add_u64 v[8:9], v[4:5], 0, s[12:13]
	global_load_dwordx2 v[68:69], v[8:9], off
	global_load_dwordx4 v[128:131], v[6:7], off offset:3584
	s_add_u32 s12, s12, 0x8000
	s_addc_u32 s13, s13, 0
	v_lshl_add_u64 v[8:9], v[4:5], 0, s[12:13]
	global_load_dwordx2 v[70:71], v[8:9], off
	global_load_dwordx4 v[132:135], v[28:29], off offset:-4096
	s_add_u32 s12, s12, 0x8000
	s_addc_u32 s13, s13, 0
	s_waitcnt vmcnt(30)
	v_cvt_pk_bf16_f32 v22, v12, v13
	v_cvt_pk_bf16_f32 v23, v14, v15
	v_lshl_add_u64 v[10:11], v[36:37], 0, s[18:19]
	global_store_dwordx2 v[10:11], v[22:23], off
	v_lshlrev_b32_e32 v24, 16, v40
	v_and_b32_e32 v25, 0xffff0000, v40
	v_lshlrev_b32_e32 v26, 16, v41
	v_and_b32_e32 v27, 0xffff0000, v41
	v_pk_fma_f32 v[12:13], v[12:13], v[72:73], v[24:25]
	v_pk_fma_f32 v[14:15], v[14:15], v[74:75], v[26:27]
	s_add_u32 s18, s18, 0x8000
	s_addc_u32 s19, s19, 0
	v_lshl_add_u64 v[8:9], v[4:5], 0, s[12:13]
	global_load_dwordx2 v[40:41], v[8:9], off
	global_load_dwordx4 v[72:75], v[28:29], off offset:-3584
	s_add_u32 s12, s12, 0x8000
	s_addc_u32 s13, s13, 0
	s_waitcnt vmcnt(31)
	v_cvt_pk_bf16_f32 v32, v12, v13
	v_cvt_pk_bf16_f32 v33, v14, v15
	v_lshl_add_u64 v[10:11], v[36:37], 0, s[18:19]
	global_store_dwordx2 v[10:11], v[32:33], off
	v_lshlrev_b32_e32 v24, 16, v42
	v_and_b32_e32 v25, 0xffff0000, v42
	v_lshlrev_b32_e32 v26, 16, v43
	v_and_b32_e32 v27, 0xffff0000, v43
	v_pk_fma_f32 v[12:13], v[12:13], v[76:77], v[24:25]
	v_pk_fma_f32 v[14:15], v[14:15], v[78:79], v[26:27]
	s_add_u32 s18, s18, 0x8000
	s_addc_u32 s19, s19, 0
	v_lshl_add_u64 v[8:9], v[4:5], 0, s[12:13]
	global_load_dwordx2 v[42:43], v[8:9], off
	global_load_dwordx4 v[76:79], v[28:29], off offset:-3072
	s_add_u32 s12, s12, 0x8000
	s_addc_u32 s13, s13, 0
	s_waitcnt vmcnt(32)
	v_cvt_pk_bf16_f32 v22, v12, v13
	v_cvt_pk_bf16_f32 v23, v14, v15
	v_lshl_add_u64 v[10:11], v[36:37], 0, s[18:19]
	global_store_dwordx2 v[10:11], v[22:23], off
	v_lshlrev_b32_e32 v24, 16, v44
	v_and_b32_e32 v25, 0xffff0000, v44
	v_lshlrev_b32_e32 v26, 16, v45
	v_and_b32_e32 v27, 0xffff0000, v45
	v_pk_fma_f32 v[12:13], v[12:13], v[80:81], v[24:25]
	v_pk_fma_f32 v[14:15], v[14:15], v[82:83], v[26:27]
	s_add_u32 s18, s18, 0x8000
	s_addc_u32 s19, s19, 0
	v_lshl_add_u64 v[8:9], v[4:5], 0, s[12:13]
	global_load_dwordx2 v[44:45], v[8:9], off
	global_load_dwordx4 v[80:83], v[28:29], off offset:-2560
	s_add_u32 s12, s12, 0x8000
	s_addc_u32 s13, s13, 0
	s_waitcnt vmcnt(33)
	v_cvt_pk_bf16_f32 v32, v12, v13
	v_cvt_pk_bf16_f32 v33, v14, v15
	v_lshl_add_u64 v[10:11], v[36:37], 0, s[18:19]
	global_store_dwordx2 v[10:11], v[32:33], off
	v_lshlrev_b32_e32 v24, 16, v46
	v_and_b32_e32 v25, 0xffff0000, v46
	v_lshlrev_b32_e32 v26, 16, v47
	v_and_b32_e32 v27, 0xffff0000, v47
	v_pk_fma_f32 v[12:13], v[12:13], v[84:85], v[24:25]
	v_pk_fma_f32 v[14:15], v[14:15], v[86:87], v[26:27]
	s_add_u32 s18, s18, 0x8000
	s_addc_u32 s19, s19, 0
	v_lshl_add_u64 v[8:9], v[4:5], 0, s[12:13]
	global_load_dwordx2 v[46:47], v[8:9], off
	global_load_dwordx4 v[84:87], v[28:29], off offset:-2048
	s_add_u32 s12, s12, 0x8000
	s_addc_u32 s13, s13, 0
	s_waitcnt vmcnt(34)
	v_cvt_pk_bf16_f32 v22, v12, v13
	v_cvt_pk_bf16_f32 v23, v14, v15
	v_lshl_add_u64 v[10:11], v[36:37], 0, s[18:19]
	global_store_dwordx2 v[10:11], v[22:23], off
	v_lshlrev_b32_e32 v24, 16, v48
	v_and_b32_e32 v25, 0xffff0000, v48
	v_lshlrev_b32_e32 v26, 16, v49
	v_and_b32_e32 v27, 0xffff0000, v49
	v_pk_fma_f32 v[12:13], v[12:13], v[88:89], v[24:25]
	v_pk_fma_f32 v[14:15], v[14:15], v[90:91], v[26:27]
	s_add_u32 s18, s18, 0x8000
	s_addc_u32 s19, s19, 0
	v_lshl_add_u64 v[8:9], v[4:5], 0, s[12:13]
	global_load_dwordx2 v[48:49], v[8:9], off
	global_load_dwordx4 v[88:91], v[28:29], off offset:-1536
	s_add_u32 s12, s12, 0x8000
	s_addc_u32 s13, s13, 0
	s_waitcnt vmcnt(35)
	v_cvt_pk_bf16_f32 v32, v12, v13
	v_cvt_pk_bf16_f32 v33, v14, v15
	v_lshl_add_u64 v[10:11], v[36:37], 0, s[18:19]
	global_store_dwordx2 v[10:11], v[32:33], off
	v_lshlrev_b32_e32 v24, 16, v50
	v_and_b32_e32 v25, 0xffff0000, v50
	v_lshlrev_b32_e32 v26, 16, v51
	v_and_b32_e32 v27, 0xffff0000, v51
	v_pk_fma_f32 v[12:13], v[12:13], v[92:93], v[24:25]
	v_pk_fma_f32 v[14:15], v[14:15], v[94:95], v[26:27]
	s_add_u32 s18, s18, 0x8000
	s_addc_u32 s19, s19, 0
	v_lshl_add_u64 v[8:9], v[4:5], 0, s[12:13]
	global_load_dwordx2 v[50:51], v[8:9], off
	global_load_dwordx4 v[92:95], v[28:29], off offset:-1024
	s_add_u32 s12, s12, 0x8000
	s_addc_u32 s13, s13, 0
	s_waitcnt vmcnt(36)
	v_cvt_pk_bf16_f32 v22, v12, v13
	v_cvt_pk_bf16_f32 v23, v14, v15
	v_lshl_add_u64 v[10:11], v[36:37], 0, s[18:19]
	global_store_dwordx2 v[10:11], v[22:23], off
	v_lshlrev_b32_e32 v24, 16, v52
	v_and_b32_e32 v25, 0xffff0000, v52
	v_lshlrev_b32_e32 v26, 16, v53
	v_and_b32_e32 v27, 0xffff0000, v53
	v_pk_fma_f32 v[12:13], v[12:13], v[96:97], v[24:25]
	v_pk_fma_f32 v[14:15], v[14:15], v[98:99], v[26:27]
	s_add_u32 s18, s18, 0x8000
	s_addc_u32 s19, s19, 0
	v_lshl_add_u64 v[8:9], v[4:5], 0, s[12:13]
	global_load_dwordx2 v[52:53], v[8:9], off
	global_load_dwordx4 v[96:99], v[28:29], off offset:-512
	s_add_u32 s12, s12, 0x8000
	s_addc_u32 s13, s13, 0
	s_waitcnt vmcnt(37)
	v_cvt_pk_bf16_f32 v32, v12, v13
	v_cvt_pk_bf16_f32 v33, v14, v15
	v_lshl_add_u64 v[10:11], v[36:37], 0, s[18:19]
	global_store_dwordx2 v[10:11], v[32:33], off
	v_lshlrev_b32_e32 v24, 16, v54
	v_and_b32_e32 v25, 0xffff0000, v54
	v_lshlrev_b32_e32 v26, 16, v55
	v_and_b32_e32 v27, 0xffff0000, v55
	v_pk_fma_f32 v[12:13], v[12:13], v[100:101], v[24:25]
	v_pk_fma_f32 v[14:15], v[14:15], v[102:103], v[26:27]
	s_add_u32 s18, s18, 0x8000
	s_addc_u32 s19, s19, 0
	v_lshl_add_u64 v[8:9], v[4:5], 0, s[12:13]
	global_load_dwordx2 v[54:55], v[8:9], off
	global_load_dwordx4 v[100:103], v[28:29], off
	s_add_u32 s12, s12, 0x8000
	s_addc_u32 s13, s13, 0
	s_waitcnt vmcnt(38)
	v_cvt_pk_bf16_f32 v22, v12, v13
	v_cvt_pk_bf16_f32 v23, v14, v15
	v_lshl_add_u64 v[10:11], v[36:37], 0, s[18:19]
	global_store_dwordx2 v[10:11], v[22:23], off
	v_lshlrev_b32_e32 v24, 16, v56
	v_and_b32_e32 v25, 0xffff0000, v56
	v_lshlrev_b32_e32 v26, 16, v57
	v_and_b32_e32 v27, 0xffff0000, v57
	v_pk_fma_f32 v[12:13], v[12:13], v[104:105], v[24:25]
	v_pk_fma_f32 v[14:15], v[14:15], v[106:107], v[26:27]
	s_add_u32 s18, s18, 0x8000
	s_addc_u32 s19, s19, 0
	v_lshl_add_u64 v[8:9], v[4:5], 0, s[12:13]
	global_load_dwordx2 v[56:57], v[8:9], off
	global_load_dwordx4 v[104:107], v[28:29], off offset:512
	s_add_u32 s12, s12, 0x8000
	s_addc_u32 s13, s13, 0
	s_waitcnt vmcnt(39)
	v_cvt_pk_bf16_f32 v32, v12, v13
	v_cvt_pk_bf16_f32 v33, v14, v15
	v_lshl_add_u64 v[10:11], v[36:37], 0, s[18:19]
	global_store_dwordx2 v[10:11], v[32:33], off
	v_lshlrev_b32_e32 v24, 16, v58
	v_and_b32_e32 v25, 0xffff0000, v58
	v_lshlrev_b32_e32 v26, 16, v59
	v_and_b32_e32 v27, 0xffff0000, v59
	v_pk_fma_f32 v[12:13], v[12:13], v[108:109], v[24:25]
	v_pk_fma_f32 v[14:15], v[14:15], v[110:111], v[26:27]
	s_add_u32 s18, s18, 0x8000
	s_addc_u32 s19, s19, 0
	v_lshl_add_u64 v[8:9], v[4:5], 0, s[12:13]
	global_load_dwordx2 v[58:59], v[8:9], off
	global_load_dwordx4 v[108:111], v[28:29], off offset:1024
	s_add_u32 s12, s12, 0x8000
	s_addc_u32 s13, s13, 0
	s_waitcnt vmcnt(40)
	v_cvt_pk_bf16_f32 v22, v12, v13
	v_cvt_pk_bf16_f32 v23, v14, v15
	v_lshl_add_u64 v[10:11], v[36:37], 0, s[18:19]
	global_store_dwordx2 v[10:11], v[22:23], off
	v_lshlrev_b32_e32 v24, 16, v60
	v_and_b32_e32 v25, 0xffff0000, v60
	v_lshlrev_b32_e32 v26, 16, v61
	v_and_b32_e32 v27, 0xffff0000, v61
	v_pk_fma_f32 v[12:13], v[12:13], v[112:113], v[24:25]
	v_pk_fma_f32 v[14:15], v[14:15], v[114:115], v[26:27]
	s_add_u32 s18, s18, 0x8000
	s_addc_u32 s19, s19, 0
	v_lshl_add_u64 v[8:9], v[4:5], 0, s[12:13]
	global_load_dwordx2 v[60:61], v[8:9], off
	global_load_dwordx4 v[112:115], v[28:29], off offset:1536
	s_add_u32 s12, s12, 0x8000
	s_addc_u32 s13, s13, 0
	s_waitcnt vmcnt(41)
	v_cvt_pk_bf16_f32 v32, v12, v13
	v_cvt_pk_bf16_f32 v33, v14, v15
	v_lshl_add_u64 v[10:11], v[36:37], 0, s[18:19]
	global_store_dwordx2 v[10:11], v[32:33], off
	v_lshlrev_b32_e32 v24, 16, v62
	v_and_b32_e32 v25, 0xffff0000, v62
	v_lshlrev_b32_e32 v26, 16, v63
	v_and_b32_e32 v27, 0xffff0000, v63
	v_pk_fma_f32 v[12:13], v[12:13], v[116:117], v[24:25]
	v_pk_fma_f32 v[14:15], v[14:15], v[118:119], v[26:27]
	s_add_u32 s18, s18, 0x8000
	s_addc_u32 s19, s19, 0
	v_lshl_add_u64 v[8:9], v[4:5], 0, s[12:13]
	global_load_dwordx2 v[62:63], v[8:9], off
	global_load_dwordx4 v[116:119], v[28:29], off offset:2048
	s_add_u32 s12, s12, 0x8000
	s_addc_u32 s13, s13, 0
	s_waitcnt vmcnt(42)
	v_cvt_pk_bf16_f32 v22, v12, v13
	v_cvt_pk_bf16_f32 v23, v14, v15
	v_lshl_add_u64 v[10:11], v[36:37], 0, s[18:19]
	global_store_dwordx2 v[10:11], v[22:23], off
	v_lshlrev_b32_e32 v24, 16, v64
	v_and_b32_e32 v25, 0xffff0000, v64
	v_lshlrev_b32_e32 v26, 16, v65
	v_and_b32_e32 v27, 0xffff0000, v65
	v_pk_fma_f32 v[12:13], v[12:13], v[120:121], v[24:25]
	v_pk_fma_f32 v[14:15], v[14:15], v[122:123], v[26:27]
	s_add_u32 s18, s18, 0x8000
	s_addc_u32 s19, s19, 0
	v_lshl_add_u64 v[8:9], v[4:5], 0, s[12:13]
	global_load_dwordx2 v[64:65], v[8:9], off
	global_load_dwordx4 v[120:123], v[28:29], off offset:2560
	s_add_u32 s12, s12, 0x8000
	s_addc_u32 s13, s13, 0
	s_waitcnt vmcnt(43)
	v_cvt_pk_bf16_f32 v32, v12, v13
	v_cvt_pk_bf16_f32 v33, v14, v15
	v_lshl_add_u64 v[10:11], v[36:37], 0, s[18:19]
	global_store_dwordx2 v[10:11], v[32:33], off
	v_lshlrev_b32_e32 v24, 16, v66
	v_and_b32_e32 v25, 0xffff0000, v66
	v_lshlrev_b32_e32 v26, 16, v67
	v_and_b32_e32 v27, 0xffff0000, v67
	v_pk_fma_f32 v[12:13], v[12:13], v[124:125], v[24:25]
	v_pk_fma_f32 v[14:15], v[14:15], v[126:127], v[26:27]
	s_add_u32 s18, s18, 0x8000
	s_addc_u32 s19, s19, 0
	v_lshl_add_u64 v[8:9], v[4:5], 0, s[12:13]
	global_load_dwordx2 v[66:67], v[8:9], off
	global_load_dwordx4 v[124:127], v[28:29], off offset:3072
	s_add_u32 s12, s12, 0x8000
	s_addc_u32 s13, s13, 0
	s_waitcnt vmcnt(44)
	v_cvt_pk_bf16_f32 v22, v12, v13
	v_cvt_pk_bf16_f32 v23, v14, v15
	v_lshl_add_u64 v[10:11], v[36:37], 0, s[18:19]
	global_store_dwordx2 v[10:11], v[22:23], off
	v_lshlrev_b32_e32 v24, 16, v68
	v_and_b32_e32 v25, 0xffff0000, v68
	v_lshlrev_b32_e32 v26, 16, v69
	v_and_b32_e32 v27, 0xffff0000, v69
	v_pk_fma_f32 v[12:13], v[12:13], v[128:129], v[24:25]
	v_pk_fma_f32 v[14:15], v[14:15], v[130:131], v[26:27]
	s_add_u32 s18, s18, 0x8000
	s_addc_u32 s19, s19, 0
	v_lshl_add_u64 v[8:9], v[4:5], 0, s[12:13]
	global_load_dwordx2 v[68:69], v[8:9], off
	global_load_dwordx4 v[128:131], v[28:29], off offset:3584
	s_add_u32 s12, s12, 0x8000
	s_addc_u32 s13, s13, 0
	s_waitcnt vmcnt(45)
	v_cvt_pk_bf16_f32 v32, v12, v13
	v_cvt_pk_bf16_f32 v33, v14, v15
	v_lshl_add_u64 v[10:11], v[36:37], 0, s[18:19]
	global_store_dwordx2 v[10:11], v[32:33], off
	v_lshlrev_b32_e32 v24, 16, v70
	v_and_b32_e32 v25, 0xffff0000, v70
	v_lshlrev_b32_e32 v26, 16, v71
	v_and_b32_e32 v27, 0xffff0000, v71
	v_pk_fma_f32 v[12:13], v[12:13], v[132:133], v[24:25]
	v_pk_fma_f32 v[14:15], v[14:15], v[134:135], v[26:27]
	s_add_u32 s18, s18, 0x8000
	s_addc_u32 s19, s19, 0
	v_lshl_add_u64 v[8:9], v[4:5], 0, s[12:13]
	global_load_dwordx2 v[70:71], v[8:9], off
	global_load_dwordx4 v[132:135], v[30:31], off offset:-4096
	s_add_u32 s12, s12, 0x8000
	s_addc_u32 s13, s13, 0
	s_waitcnt vmcnt(45)
	v_cvt_pk_bf16_f32 v22, v12, v13
	v_cvt_pk_bf16_f32 v23, v14, v15
	v_lshl_add_u64 v[10:11], v[36:37], 0, s[18:19]
	global_store_dwordx2 v[10:11], v[22:23], off
	v_lshlrev_b32_e32 v24, 16, v40
	v_and_b32_e32 v25, 0xffff0000, v40
	v_lshlrev_b32_e32 v26, 16, v41
	v_and_b32_e32 v27, 0xffff0000, v41
	v_pk_fma_f32 v[12:13], v[12:13], v[72:73], v[24:25]
	v_pk_fma_f32 v[14:15], v[14:15], v[74:75], v[26:27]
	s_add_u32 s18, s18, 0x8000
	s_addc_u32 s19, s19, 0
	s_waitcnt vmcnt(43)
	v_cvt_pk_bf16_f32 v32, v12, v13
	v_cvt_pk_bf16_f32 v33, v14, v15
	v_lshl_add_u64 v[10:11], v[36:37], 0, s[18:19]
	global_store_dwordx2 v[10:11], v[32:33], off
	v_lshlrev_b32_e32 v24, 16, v42
	v_and_b32_e32 v25, 0xffff0000, v42
	v_lshlrev_b32_e32 v26, 16, v43
	v_and_b32_e32 v27, 0xffff0000, v43
	v_pk_fma_f32 v[12:13], v[12:13], v[76:77], v[24:25]
	v_pk_fma_f32 v[14:15], v[14:15], v[78:79], v[26:27]
	s_add_u32 s18, s18, 0x8000
	s_addc_u32 s19, s19, 0
	s_waitcnt vmcnt(41)
	v_cvt_pk_bf16_f32 v22, v12, v13
	v_cvt_pk_bf16_f32 v23, v14, v15
	v_lshl_add_u64 v[10:11], v[36:37], 0, s[18:19]
	global_store_dwordx2 v[10:11], v[22:23], off
	v_lshlrev_b32_e32 v24, 16, v44
	v_and_b32_e32 v25, 0xffff0000, v44
	v_lshlrev_b32_e32 v26, 16, v45
	v_and_b32_e32 v27, 0xffff0000, v45
	v_pk_fma_f32 v[12:13], v[12:13], v[80:81], v[24:25]
	v_pk_fma_f32 v[14:15], v[14:15], v[82:83], v[26:27]
	s_add_u32 s18, s18, 0x8000
	s_addc_u32 s19, s19, 0
	s_waitcnt vmcnt(39)
	v_cvt_pk_bf16_f32 v32, v12, v13
	v_cvt_pk_bf16_f32 v33, v14, v15
	v_lshl_add_u64 v[10:11], v[36:37], 0, s[18:19]
	global_store_dwordx2 v[10:11], v[32:33], off
	v_lshlrev_b32_e32 v24, 16, v46
	v_and_b32_e32 v25, 0xffff0000, v46
	v_lshlrev_b32_e32 v26, 16, v47
	v_and_b32_e32 v27, 0xffff0000, v47
	v_pk_fma_f32 v[12:13], v[12:13], v[84:85], v[24:25]
	v_pk_fma_f32 v[14:15], v[14:15], v[86:87], v[26:27]
	s_add_u32 s18, s18, 0x8000
	s_addc_u32 s19, s19, 0
	s_waitcnt vmcnt(37)
	v_cvt_pk_bf16_f32 v22, v12, v13
	v_cvt_pk_bf16_f32 v23, v14, v15
	v_lshl_add_u64 v[10:11], v[36:37], 0, s[18:19]
	global_store_dwordx2 v[10:11], v[22:23], off
	v_lshlrev_b32_e32 v24, 16, v48
	v_and_b32_e32 v25, 0xffff0000, v48
	v_lshlrev_b32_e32 v26, 16, v49
	v_and_b32_e32 v27, 0xffff0000, v49
	v_pk_fma_f32 v[12:13], v[12:13], v[88:89], v[24:25]
	v_pk_fma_f32 v[14:15], v[14:15], v[90:91], v[26:27]
	s_add_u32 s18, s18, 0x8000
	s_addc_u32 s19, s19, 0
	s_waitcnt vmcnt(35)
	v_cvt_pk_bf16_f32 v32, v12, v13
	v_cvt_pk_bf16_f32 v33, v14, v15
	v_lshl_add_u64 v[10:11], v[36:37], 0, s[18:19]
	global_store_dwordx2 v[10:11], v[32:33], off
	v_lshlrev_b32_e32 v24, 16, v50
	v_and_b32_e32 v25, 0xffff0000, v50
	v_lshlrev_b32_e32 v26, 16, v51
	v_and_b32_e32 v27, 0xffff0000, v51
	v_pk_fma_f32 v[12:13], v[12:13], v[92:93], v[24:25]
	v_pk_fma_f32 v[14:15], v[14:15], v[94:95], v[26:27]
	s_add_u32 s18, s18, 0x8000
	s_addc_u32 s19, s19, 0
	s_waitcnt vmcnt(33)
	v_cvt_pk_bf16_f32 v22, v12, v13
	v_cvt_pk_bf16_f32 v23, v14, v15
	v_lshl_add_u64 v[10:11], v[36:37], 0, s[18:19]
	global_store_dwordx2 v[10:11], v[22:23], off
	v_lshlrev_b32_e32 v24, 16, v52
	v_and_b32_e32 v25, 0xffff0000, v52
	v_lshlrev_b32_e32 v26, 16, v53
	v_and_b32_e32 v27, 0xffff0000, v53
	v_pk_fma_f32 v[12:13], v[12:13], v[96:97], v[24:25]
	v_pk_fma_f32 v[14:15], v[14:15], v[98:99], v[26:27]
	s_add_u32 s18, s18, 0x8000
	s_addc_u32 s19, s19, 0
	s_waitcnt vmcnt(31)
	v_cvt_pk_bf16_f32 v32, v12, v13
	v_cvt_pk_bf16_f32 v33, v14, v15
	v_lshl_add_u64 v[10:11], v[36:37], 0, s[18:19]
	global_store_dwordx2 v[10:11], v[32:33], off
	v_lshlrev_b32_e32 v24, 16, v54
	v_and_b32_e32 v25, 0xffff0000, v54
	v_lshlrev_b32_e32 v26, 16, v55
	v_and_b32_e32 v27, 0xffff0000, v55
	v_pk_fma_f32 v[12:13], v[12:13], v[100:101], v[24:25]
	v_pk_fma_f32 v[14:15], v[14:15], v[102:103], v[26:27]
	s_add_u32 s18, s18, 0x8000
	s_addc_u32 s19, s19, 0
	s_waitcnt vmcnt(29)
	v_cvt_pk_bf16_f32 v22, v12, v13
	v_cvt_pk_bf16_f32 v23, v14, v15
	v_lshl_add_u64 v[10:11], v[36:37], 0, s[18:19]
	global_store_dwordx2 v[10:11], v[22:23], off
	v_lshlrev_b32_e32 v24, 16, v56
	v_and_b32_e32 v25, 0xffff0000, v56
	v_lshlrev_b32_e32 v26, 16, v57
	v_and_b32_e32 v27, 0xffff0000, v57
	v_pk_fma_f32 v[12:13], v[12:13], v[104:105], v[24:25]
	v_pk_fma_f32 v[14:15], v[14:15], v[106:107], v[26:27]
	s_add_u32 s18, s18, 0x8000
	s_addc_u32 s19, s19, 0
	s_waitcnt vmcnt(27)
	v_cvt_pk_bf16_f32 v32, v12, v13
	v_cvt_pk_bf16_f32 v33, v14, v15
	v_lshl_add_u64 v[10:11], v[36:37], 0, s[18:19]
	global_store_dwordx2 v[10:11], v[32:33], off
	v_lshlrev_b32_e32 v24, 16, v58
	v_and_b32_e32 v25, 0xffff0000, v58
	v_lshlrev_b32_e32 v26, 16, v59
	v_and_b32_e32 v27, 0xffff0000, v59
	v_pk_fma_f32 v[12:13], v[12:13], v[108:109], v[24:25]
	v_pk_fma_f32 v[14:15], v[14:15], v[110:111], v[26:27]
	s_add_u32 s18, s18, 0x8000
	s_addc_u32 s19, s19, 0
	s_waitcnt vmcnt(25)
	v_cvt_pk_bf16_f32 v22, v12, v13
	v_cvt_pk_bf16_f32 v23, v14, v15
	v_lshl_add_u64 v[10:11], v[36:37], 0, s[18:19]
	global_store_dwordx2 v[10:11], v[22:23], off
	v_lshlrev_b32_e32 v24, 16, v60
	v_and_b32_e32 v25, 0xffff0000, v60
	v_lshlrev_b32_e32 v26, 16, v61
	v_and_b32_e32 v27, 0xffff0000, v61
	v_pk_fma_f32 v[12:13], v[12:13], v[112:113], v[24:25]
	v_pk_fma_f32 v[14:15], v[14:15], v[114:115], v[26:27]
	s_add_u32 s18, s18, 0x8000
	s_addc_u32 s19, s19, 0
	s_waitcnt vmcnt(23)
	v_cvt_pk_bf16_f32 v32, v12, v13
	v_cvt_pk_bf16_f32 v33, v14, v15
	v_lshl_add_u64 v[10:11], v[36:37], 0, s[18:19]
	global_store_dwordx2 v[10:11], v[32:33], off
	v_lshlrev_b32_e32 v24, 16, v62
	v_and_b32_e32 v25, 0xffff0000, v62
	v_lshlrev_b32_e32 v26, 16, v63
	v_and_b32_e32 v27, 0xffff0000, v63
	v_pk_fma_f32 v[12:13], v[12:13], v[116:117], v[24:25]
	v_pk_fma_f32 v[14:15], v[14:15], v[118:119], v[26:27]
	s_add_u32 s18, s18, 0x8000
	s_addc_u32 s19, s19, 0
	s_waitcnt vmcnt(21)
	v_cvt_pk_bf16_f32 v22, v12, v13
	v_cvt_pk_bf16_f32 v23, v14, v15
	v_lshl_add_u64 v[10:11], v[36:37], 0, s[18:19]
	global_store_dwordx2 v[10:11], v[22:23], off
	v_lshlrev_b32_e32 v24, 16, v64
	v_and_b32_e32 v25, 0xffff0000, v64
	v_lshlrev_b32_e32 v26, 16, v65
	v_and_b32_e32 v27, 0xffff0000, v65
	v_pk_fma_f32 v[12:13], v[12:13], v[120:121], v[24:25]
	v_pk_fma_f32 v[14:15], v[14:15], v[122:123], v[26:27]
	s_add_u32 s18, s18, 0x8000
	s_addc_u32 s19, s19, 0
	s_waitcnt vmcnt(19)
	v_cvt_pk_bf16_f32 v32, v12, v13
	v_cvt_pk_bf16_f32 v33, v14, v15
	v_lshl_add_u64 v[10:11], v[36:37], 0, s[18:19]
	global_store_dwordx2 v[10:11], v[32:33], off
	v_lshlrev_b32_e32 v24, 16, v66
	v_and_b32_e32 v25, 0xffff0000, v66
	v_lshlrev_b32_e32 v26, 16, v67
	v_and_b32_e32 v27, 0xffff0000, v67
	v_pk_fma_f32 v[12:13], v[12:13], v[124:125], v[24:25]
	v_pk_fma_f32 v[14:15], v[14:15], v[126:127], v[26:27]
	s_add_u32 s18, s18, 0x8000
	s_addc_u32 s19, s19, 0
	s_waitcnt vmcnt(17)
	v_cvt_pk_bf16_f32 v22, v12, v13
	v_cvt_pk_bf16_f32 v23, v14, v15
	v_lshl_add_u64 v[10:11], v[36:37], 0, s[18:19]
	global_store_dwordx2 v[10:11], v[22:23], off
	v_lshlrev_b32_e32 v24, 16, v68
	v_and_b32_e32 v25, 0xffff0000, v68
	v_lshlrev_b32_e32 v26, 16, v69
	v_and_b32_e32 v27, 0xffff0000, v69
	v_pk_fma_f32 v[12:13], v[12:13], v[128:129], v[24:25]
	v_pk_fma_f32 v[14:15], v[14:15], v[130:131], v[26:27]
	s_add_u32 s18, s18, 0x8000
	s_addc_u32 s19, s19, 0
	s_waitcnt vmcnt(15)
	v_cvt_pk_bf16_f32 v32, v12, v13
	v_cvt_pk_bf16_f32 v33, v14, v15
	v_lshl_add_u64 v[10:11], v[36:37], 0, s[18:19]
	global_store_dwordx2 v[10:11], v[32:33], off
	v_lshlrev_b32_e32 v24, 16, v70
	v_and_b32_e32 v25, 0xffff0000, v70
	v_lshlrev_b32_e32 v26, 16, v71
	v_and_b32_e32 v27, 0xffff0000, v71
	v_pk_fma_f32 v[12:13], v[12:13], v[132:133], v[24:25]
	v_pk_fma_f32 v[14:15], v[14:15], v[134:135], v[26:27]
	s_add_u32 s18, s18, 0x8000
	s_addc_u32 s19, s19, 0
	v_add_u32_e32 v1, s2, v1
	v_cmp_lt_i32_e32 vcc, s31, v1
	s_or_b64 s[8:9], vcc, s[8:9]
	v_add_u32_e32 v16, s14, v16
	s_andn2_b64 exec, exec, s[8:9]
	s_cbranch_execnz .LBB0_615
